# code placement experiment: attention steady loop (and everything behind it) shifted by +4 bytes
# speedup vs baseline: 1.0097x; 1.0030x over previous
.LBB0_146:
	v_lshlrev_b32_e32 v34, 1, v32
	v_lshrrev_b32_e32 v32, 2, v32
	v_and_b32_e32 v215, 32, v34
	v_and_or_b32 v32, v32, 3, v218
	v_lshlrev_b32_e32 v214, 6, v32
	v_add_u32_e32 v32, 0, v215
	v_add3_u32 v221, v32, v213, v214
	v_max3_f32 v32, v0, v1, v16
	v_max3_f32 v34, v2, v3, v17
	s_and_b32 s5, s5, 0x3fffffc0
	v_max3_f32 v32, v32, v18, v19
	v_max3_f32 v34, v34, v6, v7
	s_lshl_b32 s5, s5, 2
	v_max3_f32 v32, v32, v4, v5
	v_max3_f32 v34, v34, v22, v23
	s_add_i32 s6, s5, 0
	v_max3_f32 v32, v32, v20, v21
	v_max3_f32 v34, v34, v10, v11
	s_cmp_lg_u32 0, -1
	v_max3_f32 v32, v32, v8, v9
	v_max3_f32 v34, v34, v26, v27
	s_mov_b64 s[14:15], 0x20000
	v_max3_f32 v32, v32, v24, v25
	v_max3_f32 v34, v34, v14, v15
	s_mov_b32 s36, 1
	v_max3_f32 v32, v32, v12, v13
	v_max3_f32 v34, v34, v30, v31
	s_mov_b32 s28, 0
	v_max3_f32 v32, v32, v28, v29
	v_lshl_add_u32 v217, v211, 2, s6
	v_max_f32_e32 v32, v32, v34
	v_lshl_add_u32 v216, v218, 2, s6
	v_mov_b32_e32 v34, v32
	s_nop 1
	v_permlane32_swap_b32_e32 v32, v34
	v_max_f32_e32 v32, v32, v34
	s_nop 0
	v_sub_f32_e32 v0, v0, v32
	v_sub_f32_e32 v1, v1, v32
	v_sub_f32_e32 v2, v2, v32
	v_sub_f32_e32 v3, v3, v32
	v_sub_f32_e32 v4, v4, v32
	v_sub_f32_e32 v5, v5, v32
	v_sub_f32_e32 v6, v6, v32
	v_sub_f32_e32 v7, v7, v32
	v_sub_f32_e32 v8, v8, v32
	v_sub_f32_e32 v9, v9, v32
	v_sub_f32_e32 v10, v10, v32
	v_sub_f32_e32 v11, v11, v32
	v_sub_f32_e32 v12, v12, v32
	v_sub_f32_e32 v13, v13, v32
	v_sub_f32_e32 v14, v14, v32
	v_sub_f32_e32 v15, v15, v32
	v_sub_f32_e32 v34, v16, v32
	v_sub_f32_e32 v35, v17, v32
	v_sub_f32_e32 v36, v18, v32
	v_sub_f32_e32 v37, v19, v32
	v_sub_f32_e32 v38, v20, v32
	v_sub_f32_e32 v39, v21, v32
	v_sub_f32_e32 v40, v22, v32
	v_sub_f32_e32 v41, v23, v32
	v_sub_f32_e32 v42, v24, v32
	v_sub_f32_e32 v43, v25, v32
	v_sub_f32_e32 v44, v26, v32
	v_sub_f32_e32 v45, v27, v32
	v_sub_f32_e32 v46, v28, v32
	v_sub_f32_e32 v47, v29, v32
	v_sub_f32_e32 v48, v30, v32
	v_sub_f32_e32 v49, v31, v32
	s_nop 0
	v_exp_f32_e32 v80, v0
	v_exp_f32_e32 v81, v1
	v_exp_f32_e32 v82, v2
	v_exp_f32_e32 v83, v3
	v_exp_f32_e32 v84, v4
	v_exp_f32_e32 v85, v5
	v_exp_f32_e32 v86, v6
	v_exp_f32_e32 v87, v7
	v_exp_f32_e32 v88, v8
	v_exp_f32_e32 v89, v9
	v_exp_f32_e32 v90, v10
	v_exp_f32_e32 v91, v11
	v_exp_f32_e32 v92, v12
	v_exp_f32_e32 v93, v13
	v_exp_f32_e32 v94, v14
	v_exp_f32_e32 v95, v15
	ds_read_b128 v[0:3], v33 offset:256
	ds_read_b128 v[4:7], v33 offset:288
	ds_read_b128 v[8:11], v33 offset:384
	ds_read_b128 v[12:15], v33 offset:416
	ds_read_b128 v[16:19], v33 offset:320
	ds_read_b128 v[20:23], v33 offset:352
	ds_read_b128 v[24:27], v33 offset:448
	ds_read_b128 v[28:31], v33 offset:480
	s_waitcnt vmcnt(0) lgkmcnt(0)
	s_barrier
	v_add_f32_e32 v204, v193, v32
	v_exp_f32_e32 v32, v34
	s_waitcnt lgkmcnt(7)
	v_sub_f32_e32 v65, v1, v204
	v_sub_f32_e32 v64, v0, v204
	v_lshl_add_u64 v[0:1], v[206:207], 0, s[48:49]
	s_mov_b32 m0, s18
	s_nop 0
	global_load_lds_dwordx4 v[0:1], off
	s_cselect_b32 s5, 0, 0
	s_add_i32 s4, s5, s4
	v_lshl_add_u64 v[0:1], v[208:209], 0, s[14:15]
	s_add_i32 s4, s4, 0x8000
	s_mov_b32 m0, s4
	s_nop 0
	global_load_lds_dwordx4 v[0:1], off
	ds_read_b128 v[156:159], v220 offset:8192
	ds_read_b128 v[152:155], v220 offset:8704
	ds_read_b128 v[148:151], v220 offset:10240
	ds_read_b128 v[144:147], v220 offset:10752
	ds_read_b128 v[140:143], v220 offset:12288
	ds_read_b128 v[132:135], v220 offset:12800
	ds_read_b128 v[136:139], v220 offset:14336
	ds_read_b128 v[128:131], v220 offset:14848
	v_exp_f32_e32 v33, v35
	v_exp_f32_e32 v34, v36
	v_exp_f32_e32 v35, v37
	v_exp_f32_e32 v36, v38
	v_exp_f32_e32 v37, v39
	v_exp_f32_e32 v38, v40
	v_exp_f32_e32 v39, v41
	v_exp_f32_e32 v40, v42
	v_exp_f32_e32 v41, v43
	v_exp_f32_e32 v42, v44
	v_exp_f32_e32 v43, v45
	v_exp_f32_e32 v44, v46
	v_exp_f32_e32 v45, v47
	v_exp_f32_e32 v46, v48
	v_exp_f32_e32 v47, v49
	s_waitcnt vmcnt(2) lgkmcnt(0)
	s_barrier
	s_waitcnt lgkmcnt(10)
	v_sub_f32_e32 v79, v23, v204
	v_sub_f32_e32 v78, v22, v204
	v_sub_f32_e32 v77, v21, v204
	v_sub_f32_e32 v76, v20, v204
	v_sub_f32_e32 v75, v19, v204
	v_sub_f32_e32 v74, v18, v204
	v_sub_f32_e32 v73, v17, v204
	v_sub_f32_e32 v72, v16, v204
	v_sub_f32_e32 v71, v7, v204
	v_sub_f32_e32 v70, v6, v204
	v_sub_f32_e32 v69, v5, v204
	v_sub_f32_e32 v68, v4, v204
	v_sub_f32_e32 v67, v3, v204
	v_sub_f32_e32 v66, v2, v204
	s_waitcnt lgkmcnt(8)
	v_sub_f32_e32 v63, v31, v204
	v_sub_f32_e32 v62, v30, v204
	v_sub_f32_e32 v61, v29, v204
	v_sub_f32_e32 v60, v28, v204
	v_sub_f32_e32 v59, v27, v204
	v_sub_f32_e32 v58, v26, v204
	v_sub_f32_e32 v57, v25, v204
	v_sub_f32_e32 v56, v24, v204
	v_sub_f32_e32 v55, v15, v204
	v_sub_f32_e32 v54, v14, v204
	v_sub_f32_e32 v53, v13, v204
	v_sub_f32_e32 v52, v12, v204
	v_sub_f32_e32 v51, v11, v204
	v_sub_f32_e32 v50, v10, v204
	v_sub_f32_e32 v49, v9, v204
	v_sub_f32_e32 v48, v8, v204
	s_cmp_lt_i32 s20, 7
	v_cmp_gt_u32_e64 s[4:5], 32, v197
	s_cbranch_scc1 .LBB0_165
	s_add_i32 s6, s17, 0
	s_add_i32 s6, s6, 0x14a00
	v_mov_b32_e32 v16, v193
	v_mov_b32_e32 v17, v193
	v_lshl_add_u32 v180, v212, 4, s6
	s_mov_b64 s[6:7], 0xa0000
	v_mov_b32_e32 v18, v193
	v_mov_b32_e32 v19, v193
	v_mov_b32_e32 v20, v193
	v_mov_b32_e32 v21, v193
	v_mov_b32_e32 v22, v193
	v_mov_b32_e32 v23, v193
	v_mov_b32_e32 v24, v193
	v_mov_b32_e32 v25, v193
	v_mov_b32_e32 v26, v193
	v_mov_b32_e32 v27, v193
	v_mov_b32_e32 v28, v193
	v_mov_b32_e32 v29, v193
	v_mov_b32_e32 v30, v193
	v_mov_b32_e32 v31, v193
	v_mov_b64_e32 v[0:1], v[16:17]
	v_lshl_add_u64 v[176:177], v[208:209], 0, s[48:49]
	v_lshl_add_u64 v[178:179], v[206:207], 0, s[6:7]
	s_mov_b32 s6, 0
	s_movk_i32 s28, 0x4000
	s_movk_i32 s41, 0x2000
	v_mov_b32_e32 v222, 0
	s_mov_b32 s36, 6
	v_mov_b64_e32 v[2:3], v[18:19]
	v_mov_b64_e32 v[4:5], v[20:21]
	v_mov_b64_e32 v[6:7], v[22:23]
	v_mov_b64_e32 v[8:9], v[24:25]
	v_mov_b64_e32 v[10:11], v[26:27]
	v_mov_b64_e32 v[12:13], v[28:29]
	v_mov_b64_e32 v[14:15], v[30:31]
	s_nop 0
